# MLA loop: V-tile LDS-DMA issue hoisted from the middle of the QK section to the loop head (same instructions, earlier issue)
# baseline (speedup 1.0000x reference)
.LBB0_350:
	s_add_i32 s0, s2, -1
	s_and_b32 s3, s0, 1
	s_xor_b32 s0, s3, 1
	s_mulk_i32 s0, 0x5100
	v_add_u32_e32 v84, s0, v197
	ds_read_b128 v[18:21], v84
	ds_read_b128 v[22:25], v84 offset:512
	s_mov_b32 m0, s101
	v_ashrrev_i32_e32 v115, 31, v114
	global_load_lds_dwordx4 v[216:217], off
	v_lshlrev_b64 v[26:27], 11, v[114:115]
	s_add_i32 m0, s101, 0x2f80
	v_lshl_add_u64 v[26:27], v[30:31], 0, v[26:27]
	global_load_lds_dwordx4 v[26:27], off offset:128
	s_and_b64 vcc, exec, s[38:39]
	s_cbranch_vccnz .LBB0_352
	s_add_i32 m0, s101, 0x2000
	s_nop 0
	global_load_lds_dwordx4 v[218:219], off
.LBB0_352:
	s_waitcnt lgkmcnt(1)
	v_mfma_f32_32x32x16_bf16 v[2:17], v[18:21], v[116:119], v[96:111]
	s_waitcnt lgkmcnt(0)
	v_mfma_f32_32x32x16_bf16 v[64:79], v[22:25], v[116:119], v[96:111]
	ds_read_b128 v[18:21], v84 offset:2048
	ds_read_b128 v[22:25], v84 offset:2560
	s_waitcnt lgkmcnt(0)
	v_mfma_f32_32x32x16_bf16 v[64:79], v[22:25], v[120:123], v[64:79]
	v_mfma_f32_32x32x16_bf16 v[2:17], v[18:21], v[120:123], v[2:17]
	ds_read_b128 v[18:21], v84 offset:4096
	ds_read_b128 v[22:25], v84 offset:4608
	s_waitcnt lgkmcnt(0)
	v_mfma_f32_32x32x16_bf16 v[64:79], v[22:25], v[124:127], v[64:79]
	v_mfma_f32_32x32x16_bf16 v[2:17], v[18:21], v[124:127], v[2:17]
	ds_read_b128 v[18:21], v84 offset:6144
	ds_read_b128 v[22:25], v84 offset:6656
	s_waitcnt lgkmcnt(0)
	v_mfma_f32_32x32x16_bf16 v[64:79], v[22:25], v[128:131], v[64:79]
	ds_read_b128 v[22:25], v84 offset:8704
	ds_read_b128 v[26:29], v84 offset:10240
	v_add_u32_e32 v115, s0, v196
	v_mfma_f32_32x32x16_bf16 v[2:17], v[18:21], v[128:131], v[2:17]
	ds_read_b128 v[18:21], v84 offset:8192
	s_waitcnt lgkmcnt(0)
	v_mfma_f32_32x32x16_bf16 v[2:17], v[18:21], v[132:135], v[2:17]
	ds_read_b64_tr_b16 v[152:153], v115 offset:12288
	ds_read_b64_tr_b16 v[154:155], v115 offset:12800
	ds_read_b64_tr_b16 v[88:89], v115 offset:13312
	ds_read_b64_tr_b16 v[90:91], v115 offset:13824
	ds_read_b64_tr_b16 v[80:81], v115 offset:14336
	ds_read_b64_tr_b16 v[82:83], v115 offset:14848
	ds_read_b64_tr_b16 v[18:19], v115 offset:15360
	ds_read_b64_tr_b16 v[20:21], v115 offset:15872
	ds_read_b128 v[200:203], v84 offset:10752
	v_mfma_f32_32x32x16_bf16 v[64:79], v[22:25], v[132:135], v[64:79]
	v_mfma_f32_32x32x16_bf16 v[2:17], v[26:29], v[136:139], v[2:17]
	ds_read_b64_tr_b16 v[92:93], v115 offset:16384
	ds_read_b64_tr_b16 v[94:95], v115 offset:16896
	ds_read_b64_tr_b16 v[84:85], v115 offset:17408
	ds_read_b64_tr_b16 v[86:87], v115 offset:17920
	ds_read_b64_tr_b16 v[26:27], v115 offset:18432
	ds_read_b64_tr_b16 v[28:29], v115 offset:18944
	ds_read_b64_tr_b16 v[22:23], v115 offset:19456
	ds_read_b64_tr_b16 v[24:25], v115 offset:19968
	s_waitcnt lgkmcnt(8)
	v_mfma_f32_32x32x16_bf16 v[64:79], v[200:203], v[136:139], v[64:79]
	v_max3_f32 v115, v2, v3, v64
	v_max3_f32 v171, v4, v5, v65
	v_max3_f32 v115, v115, v66, v67
	v_max3_f32 v171, v171, v8, v9
	v_max3_f32 v115, v115, v6, v7
	v_max3_f32 v171, v171, v70, v71
	v_max3_f32 v115, v115, v68, v69
	v_max3_f32 v171, v171, v12, v13
	v_max3_f32 v115, v115, v10, v11
	v_max3_f32 v171, v171, v74, v75
	v_max3_f32 v115, v115, v72, v73
	v_max3_f32 v171, v171, v16, v17
	v_max3_f32 v115, v115, v14, v15
	v_max3_f32 v171, v171, v78, v79
	v_max3_f32 v115, v115, v76, v77
	v_max_f32_e32 v115, v115, v171
	v_mov_b32_e32 v171, v115
	s_nop 1
	v_permlane32_swap_b32_e32 v115, v171
	v_max_f32_e32 v115, v115, v171
	v_cmp_lt_f32_e32 vcc, s75, v115
	s_cbranch_vccz .LBB0_356
	v_max_f32_e32 v96, v115, v115
	v_max_f32_e32 v98, 0, v96
	v_exp_f32_e64 v115, -v98
	s_and_saveexec_b64 s[0:1], s[40:41]
	ds_write_b32 v198, v115 offset:41472
	s_or_b64 exec, exec, s[0:1]
	s_waitcnt lgkmcnt(0)
	ds_read_b128 v[200:203], v1 offset:41472
	ds_read_b128 v[204:207], v1 offset:41504
	ds_read_b128 v[208:211], v1 offset:41536
	ds_read_b128 v[212:215], v1 offset:41568
	v_add_f32_e32 v0, v0, v98
	s_waitcnt lgkmcnt(0)
	v_xor_b32_e32 v96, 0x80000000, v0
	v_pk_add_f32 v[2:3], v[2:3], v[98:99] op_sel_hi:[1,0] neg_lo:[0,1] neg_hi:[0,1]
	v_pk_add_f32 v[64:65], v[64:65], v[98:99] op_sel_hi:[1,0] neg_lo:[0,1] neg_hi:[0,1]
	v_pk_add_f32 v[4:5], v[4:5], v[98:99] op_sel_hi:[1,0] neg_lo:[0,1] neg_hi:[0,1]
	v_pk_add_f32 v[66:67], v[66:67], v[98:99] op_sel_hi:[1,0] neg_lo:[0,1] neg_hi:[0,1]
	v_pk_add_f32 v[6:7], v[6:7], v[98:99] op_sel_hi:[1,0] neg_lo:[0,1] neg_hi:[0,1]
	v_pk_add_f32 v[68:69], v[68:69], v[98:99] op_sel_hi:[1,0] neg_lo:[0,1] neg_hi:[0,1]
	v_pk_add_f32 v[8:9], v[8:9], v[98:99] op_sel_hi:[1,0] neg_lo:[0,1] neg_hi:[0,1]
	v_pk_add_f32 v[70:71], v[70:71], v[98:99] op_sel_hi:[1,0] neg_lo:[0,1] neg_hi:[0,1]
	v_pk_add_f32 v[10:11], v[10:11], v[98:99] op_sel_hi:[1,0] neg_lo:[0,1] neg_hi:[0,1]
	v_pk_add_f32 v[72:73], v[72:73], v[98:99] op_sel_hi:[1,0] neg_lo:[0,1] neg_hi:[0,1]
	v_pk_add_f32 v[12:13], v[12:13], v[98:99] op_sel_hi:[1,0] neg_lo:[0,1] neg_hi:[0,1]
	v_pk_add_f32 v[74:75], v[74:75], v[98:99] op_sel_hi:[1,0] neg_lo:[0,1] neg_hi:[0,1]
	v_pk_add_f32 v[14:15], v[14:15], v[98:99] op_sel_hi:[1,0] neg_lo:[0,1] neg_hi:[0,1]
	v_pk_add_f32 v[76:77], v[76:77], v[98:99] op_sel_hi:[1,0] neg_lo:[0,1] neg_hi:[0,1]
	v_pk_add_f32 v[16:17], v[16:17], v[98:99] op_sel_hi:[1,0] neg_lo:[0,1] neg_hi:[0,1]
	v_pk_add_f32 v[78:79], v[78:79], v[98:99] op_sel_hi:[1,0] neg_lo:[0,1] neg_hi:[0,1]
	v_mov_b32_e32 v97, v96
	v_mov_b32_e32 v98, v96
	v_mov_b32_e32 v99, v96
	v_mov_b32_e32 v100, v96
	v_mov_b32_e32 v101, v96
	v_mov_b32_e32 v102, v96
	v_mov_b32_e32 v103, v96
	v_mov_b32_e32 v104, v96
	v_mov_b32_e32 v105, v96
	v_mov_b32_e32 v106, v96
	v_mov_b32_e32 v107, v96
	v_mov_b32_e32 v108, v96
	v_mov_b32_e32 v109, v96
	v_mov_b32_e32 v110, v96
	v_mov_b32_e32 v111, v96
	v_mul_f32_e32 v163, v163, v115
	s_waitcnt lgkmcnt(0)
	v_pk_mul_f32 v[46:47], v[46:47], v[214:215]
	v_pk_mul_f32 v[42:43], v[42:43], v[210:211]
	v_pk_mul_f32 v[38:39], v[38:39], v[206:207]
	v_pk_mul_f32 v[34:35], v[34:35], v[202:203]
	v_pk_mul_f32 v[44:45], v[44:45], v[212:213]
	v_pk_mul_f32 v[40:41], v[40:41], v[208:209]
	v_pk_mul_f32 v[36:37], v[36:37], v[204:205]
	v_pk_mul_f32 v[32:33], v[32:33], v[200:201]
	v_pk_mul_f32 v[62:63], v[62:63], v[214:215]
	v_pk_mul_f32 v[58:59], v[58:59], v[210:211]
	v_pk_mul_f32 v[54:55], v[54:55], v[206:207]
	v_pk_mul_f32 v[50:51], v[50:51], v[202:203]
	v_pk_mul_f32 v[60:61], v[60:61], v[212:213]
	v_pk_mul_f32 v[56:57], v[56:57], v[208:209]
	v_pk_mul_f32 v[52:53], v[52:53], v[204:205]
	v_pk_mul_f32 v[48:49], v[48:49], v[200:201]
